# PREP weight transposes (f1g,f1u) done by a hand-written LDS-free transposer (16B loads, in-lane bf16 packing, double buffered); plus PAPR round-2 split
# speedup vs baseline: 1.0011x; 1.0011x over previous
.LBB0_85:
	s_or_b64 exec, exec, s[6:7]
	v_readfirstlane_b32 s88, v128
	s_lshr_b32 s88, s88, 6
	s_lshl_b32 s87, s34, 3
	s_add_u32 s65, s87, s88
	s_lshl_b32 s66, s94, 3
	s_mov_b32 s64, 0
	s_mov_b32 s68, 0x1600
	s_mov_b32 s67, 0
	s_branch .LT_entry
.LT_ret0:
	s_sub_u32 s65, s65, s68
	s_mov_b32 s64, 1
	s_mov_b32 s68, 0x1600
	s_mov_b32 s67, 1
	s_branch .LT_entry

.LBB0_154:
.LBB0_155:
	s_cmp_lt_i32 s92, 2
	s_cselect_b64 s[0:1], -1, 0
	s_cmp_gt_i32 s93, 1
	s_cselect_b64 s[4:5], -1, 0
	s_and_b64 s[4:5], s[0:1], s[4:5]
	s_andn2_b64 vcc, exec, s[4:5]
	s_cbranch_vccnz .LBB0_269
	s_andn2_b64 vcc, exec, s[2:3]
	s_cbranch_vccnz .LBB0_210
	s_waitcnt vmcnt(0)
	s_barrier
	s_mov_b64 s[2:3], exec
	v_readlane_b32 s4, v235, 17
	v_readlane_b32 s5, v235, 18
	s_and_b64 s[4:5], s[2:3], s[4:5]
	s_mov_b64 exec, s[4:5]
	s_cbranch_execz .LBB0_209
	s_add_i32 s4, 0, 0x23ff0
	v_mov_b32_e32 v0, s4
	s_waitcnt vmcnt(0) expcnt(0) lgkmcnt(0)
	ds_read_b32 v2, v0
	s_add_i32 s4, 0, 0x23ff4
	v_mov_b32_e32 v0, s4
	ds_read_b32 v0, v0
	s_waitcnt lgkmcnt(1)
	v_cmp_ne_u32_e32 vcc, 0, v2
	s_cbranch_vccnz .LBB0_173
	v_readlane_b32 s4, v235, 0
	s_mul_i32 s28, s95, s4
	s_add_u32 s4, s50, 0x1000
	s_addc_u32 s5, s51, 0
	s_add_u32 s6, s50, 0x1100
	s_addc_u32 s7, s51, 0
	s_add_u32 s8, s50, 0x1200
	s_addc_u32 s9, s51, 0
	s_add_u32 s10, s50, 0x1300
	s_mul_i32 s28, s28, s94
	s_addc_u32 s11, s51, 0
	s_mov_b32 s29, 1
	v_mov_b32_e32 v16, 0
	s_branch .LBB0_161

.LT_done:
	s_cmp_eq_u32 s67, 0
	s_cbranch_scc1 .LT_ret0
	s_cmp_eq_u32 s67, 1
	s_cbranch_scc1 .LT_ret1
	s_endpgm
